# attention units assigned statically by census rank (two per CU), queue atomics only for the remaining items
# baseline (speedup 1.0000x reference)
.LBB0_321:
	s_or_b64 exec, exec, s[6:7]
	s_load_dwordx2 s[12:13], s[0:1], 0xc8
	s_ashr_i32 s10, s3, 6
	v_and_b32_e32 v201, 63, v200
	s_mov_b32 s79, 0
	s_mov_b32 s101, 0
	v_cmp_eq_u32_e64 s[6:7], 0, v200
	s_waitcnt lgkmcnt(0)
	s_add_u32 s85, s12, 0x5c00000
	s_addc_u32 s93, s13, 0
	s_add_u32 s4, s12, 0x6d00000
	v_writelane_b32 v255, s4, 57
	s_addc_u32 s4, s13, 0
	v_writelane_b32 v255, s4, 59
	s_add_u32 s4, s12, 0x7200000
	v_writelane_b32 v255, s4, 60
	s_addc_u32 s4, s13, 0
	s_cmp_lg_u32 s66, -1
	v_writelane_b32 v255, s4, 61
	s_cselect_b32 s56, s66, 0
	s_or_b32 s4, s37, s23
	s_ashr_i32 s5, s4, 31
	s_lshl_b64 s[4:5], s[4:5], 2
	s_add_u32 s4, s12, s4
	s_addc_u32 s5, s13, s5
	s_add_u32 s4, s4, 0x3800
	v_writelane_b32 v255, s4, 62
	s_addc_u32 s4, s5, 0
	v_writelane_b32 v255, s4, 63
	s_mul_i32 s4, s10, 0x1100
	s_add_i32 s77, s4, 0
	s_and_b32 s18, s3, 0xffffffc0
	s_add_i32 s77, s77, 0x1a400
	s_ashr_i32 s19, s18, 31
	v_readlane_b32 s4, v255, 36
	v_readlane_b32 s5, v255, 37
	s_add_u32 s3, s12, s4
	s_addc_u32 s8, s13, s5
	s_lshl_b32 s4, s10, 12
	s_ashr_i32 s5, s4, 31
	s_lshl_b64 s[4:5], s[4:5], 1
	s_add_u32 s3, s3, s4
	s_addc_u32 s4, s8, s5
	s_add_u32 s78, s3, 0x300000
	s_addc_u32 s42, s4, 0
	s_add_u32 s20, s12, 0x600000
	s_addc_u32 s21, s13, 0
	s_lshl_b32 s3, s10, 9
	s_lshl_b32 s8, s10, 10
	s_add_i32 s76, s3, 0
	s_ashr_i32 s9, s8, 31
	s_add_i32 s76, s76, 0x22c00
	s_lshl_b64 s[4:5], s[18:19], 1
	s_add_u32 s3, s12, s4
	s_addc_u32 s5, s13, s5
	s_add_u32 s4, s3, 0x7700000
	s_addc_u32 s5, s5, 0
	s_add_u32 s22, s12, 0x400000
	s_addc_u32 s23, s13, 0
	s_add_i32 s67, s56, 0x6000
	s_lshl_b64 s[8:9], s[8:9], 2
	s_add_u32 s3, s12, s8
	s_addc_u32 s8, s13, s9
	s_add_u32 s24, s3, 0xbb00800
	s_addc_u32 s25, s8, 0
	s_barrier
	s_branch .LBB0_323
.LBB0_322:
	s_add_i32 s79, s79, 1
	s_cmp_eq_u32 s79, 8
	s_cbranch_scc1 .LBB0_419
	s_cmp_lg_u32 s79, 1
	s_cbranch_scc1 .Lq_mask_ready
	s_cmp_lg_u64 s[6:7], 0
	s_cbranch_scc0 .Lq_skipload
	s_mov_b64 s[8:9], exec
	s_mov_b64 exec, 0xff
	v_lshlrev_b32_e32 v2, 8, v228
	v_readlane_b32 s10, v255, 62
	v_readlane_b32 s11, v255, 63
	s_nop 4
	global_load_dword v3, v2, s[10:11] sc1
	s_waitcnt vmcnt(0)
	v_add_u32_e32 v3, 64, v3
	v_cmp_le_i32_e32 vcc, s2, v3
	s_mov_b64 exec, s[8:9]
	s_nop 1
	v_mov_b32_e32 v2, vcc_lo
	v_mov_b32_e32 v3, s61
	ds_write_b32 v3, v2

.LBB0_327:
	s_barrier
	s_and_saveexec_b64 s[8:9], s[6:7]
	s_cbranch_execz .LBB0_331
	s_mov_b64 s[12:13], exec
	v_mbcnt_lo_u32_b32 v0, s12, 0
	v_mbcnt_hi_u32_b32 v0, s13, v0
	v_cmp_eq_u32_e32 vcc, 0, v0
	s_and_saveexec_b64 s[10:11], vcc
	s_cbranch_execz .LBB0_330
	s_bcnt1_i32_b64 s3, s[12:13]
	s_waitcnt vmcnt(0)
	s_cmp_lg_u32 s79, 0
	s_cbranch_scc1 .Lsp_dyn
	s_cmp_gt_u32 s101, 1
	s_cbranch_scc1 .Lsp_dyn
	v_mov_b32_e32 v2, 0x23fc8
	ds_read_b32 v2, v2
	s_lshl_b32 vcc_lo, s101, 5
	s_add_i32 s101, s101, 1
	s_waitcnt lgkmcnt(0)
	s_branch .LBB0_330
.Lsp_dyn:
	v_mov_b32_e32 v2, s3
	global_atomic_add v2, v1, v2, s[26:27] sc0
	s_movk_i32 vcc_lo, 64
.LBB0_330:
	s_or_b64 exec, exec, s[10:11]
	s_waitcnt vmcnt(0)
	v_readfirstlane_b32 s3, v2
	s_add_i32 s3, s3, vcc_lo
	v_mov_b32_e32 v2, s61
	s_nop 0
	v_add_u32_e32 v0, s3, v0
	ds_write_b32 v2, v0
